# v22 + nt hint on the prologue's read-once f32 weight loads (weight transposition loop)
# speedup vs baseline: 1.0056x; 1.0056x over previous
; __device__ __forceinline__ void titem_load(float (&tv)[32], const TItem& t, int lane) {
;     const float* wp = t.W + (size_t)(t.k0 + (lane >> 5)) * t.N + t.n0 + (lane & 31); const size_t st = (size_t)2 * t.N;
; #pragma unroll
;     for (int i = 0; i < 32; ++i) tv[i] = wp[(size_t)i * st];
; }
; __device__ __forceinline__ void phase_prologue(const P& p, LAS unsigned char* lds, int gw, int NGW, int lane, int wave) {
;     ...
;     for (int it = gw; it < DEPTH * IT_L; it += 2 * NGW) {
;         TItem a, b2; titem_decode(a, p, ws, it, IT_L); const bool hb = it + NGW < DEPTH * IT_L; titem_decode(b2, p, ws, hb ? it + NGW : it, IT_L);
;         float ta[32], tb[32];
;         titem_load(ta, a, lane); if (hb) titem_load(tb, b2, lane);
;         titem_store(ta, a, scr, lane); if (hb) titem_store(tb, b2, scr, lane);
.LBB0_54:
	v_add_u32_e32 v45, s8, v7
	v_ashrrev_i32_e32 v46, 31, v45
	v_mul_lo_u32 v48, s20, v46
	v_mul_lo_u32 v49, s21, v45
	v_mad_u64_u32 v[46:47], s[28:29], s20, v45, 0
	v_add3_u32 v47, v47, v48, v49
	v_lshl_add_u64 v[46:47], v[46:47], 2, s[0:1]
	s_ashr_i32 s19, s18, 31
	v_lshl_add_u64 v[46:47], s[18:19], 2, v[46:47]
	v_lshl_add_u64 v[46:47], v[46:47], 0, v[4:5]
	s_lshl_b64 s[0:1], s[20:21], 3
	v_lshl_add_u64 v[48:49], v[46:47], 0, s[0:1]
	global_load_dword v45, v[46:47], off nt
	s_andn2_b64 vcc, exec, s[22:23]
	global_load_dword v46, v[48:49], off nt
	v_lshl_add_u64 v[48:49], v[48:49], 0, s[0:1]
	v_lshl_add_u64 v[50:51], v[48:49], 0, s[0:1]
	global_load_dword v47, v[48:49], off nt
	s_nop 0
	global_load_dword v48, v[50:51], off nt
	v_lshl_add_u64 v[50:51], v[50:51], 0, s[0:1]
	v_lshl_add_u64 v[52:53], v[50:51], 0, s[0:1]
	global_load_dword v49, v[50:51], off nt
	s_nop 0
	global_load_dword v50, v[52:53], off nt
	v_lshl_add_u64 v[52:53], v[52:53], 0, s[0:1]
	v_lshl_add_u64 v[54:55], v[52:53], 0, s[0:1]
	global_load_dword v51, v[52:53], off nt
	s_nop 0
	global_load_dword v52, v[54:55], off nt
	v_lshl_add_u64 v[54:55], v[54:55], 0, s[0:1]
	v_lshl_add_u64 v[56:57], v[54:55], 0, s[0:1]
	global_load_dword v53, v[54:55], off nt
	s_nop 0
	global_load_dword v54, v[56:57], off nt
	v_lshl_add_u64 v[56:57], v[56:57], 0, s[0:1]
	v_lshl_add_u64 v[58:59], v[56:57], 0, s[0:1]
	global_load_dword v55, v[56:57], off nt
	s_nop 0
	global_load_dword v56, v[58:59], off nt
	v_lshl_add_u64 v[58:59], v[58:59], 0, s[0:1]
	v_lshl_add_u64 v[60:61], v[58:59], 0, s[0:1]
	global_load_dword v57, v[58:59], off nt
	s_nop 0
	global_load_dword v58, v[60:61], off nt
	v_lshl_add_u64 v[60:61], v[60:61], 0, s[0:1]
	v_lshl_add_u64 v[62:63], v[60:61], 0, s[0:1]
	global_load_dword v59, v[60:61], off nt
	s_nop 0
	global_load_dword v60, v[62:63], off nt
	v_lshl_add_u64 v[62:63], v[62:63], 0, s[0:1]
	v_lshl_add_u64 v[64:65], v[62:63], 0, s[0:1]
	global_load_dword v61, v[62:63], off nt
	s_nop 0
	global_load_dword v62, v[64:65], off nt
	v_lshl_add_u64 v[64:65], v[64:65], 0, s[0:1]
	v_lshl_add_u64 v[66:67], v[64:65], 0, s[0:1]
	global_load_dword v63, v[64:65], off nt
	s_nop 0
	global_load_dword v64, v[66:67], off nt
	v_lshl_add_u64 v[66:67], v[66:67], 0, s[0:1]
	v_lshl_add_u64 v[68:69], v[66:67], 0, s[0:1]
	global_load_dword v65, v[66:67], off nt
	s_nop 0
	global_load_dword v66, v[68:69], off nt
	v_lshl_add_u64 v[68:69], v[68:69], 0, s[0:1]
	v_lshl_add_u64 v[70:71], v[68:69], 0, s[0:1]
	global_load_dword v67, v[68:69], off nt
	s_nop 0
	global_load_dword v68, v[70:71], off nt
	v_lshl_add_u64 v[70:71], v[70:71], 0, s[0:1]
	v_lshl_add_u64 v[72:73], v[70:71], 0, s[0:1]
	global_load_dword v69, v[70:71], off nt
	s_nop 0
	global_load_dword v70, v[72:73], off nt
	v_lshl_add_u64 v[72:73], v[72:73], 0, s[0:1]
	v_lshl_add_u64 v[74:75], v[72:73], 0, s[0:1]
	global_load_dword v71, v[72:73], off nt
	s_nop 0
	global_load_dword v72, v[74:75], off nt
	v_lshl_add_u64 v[74:75], v[74:75], 0, s[0:1]
	v_lshl_add_u64 v[76:77], v[74:75], 0, s[0:1]
	global_load_dword v73, v[74:75], off nt
	s_nop 0
	global_load_dword v74, v[76:77], off nt
	v_lshl_add_u64 v[76:77], v[76:77], 0, s[0:1]
	global_load_dword v75, v[76:77], off nt
	v_lshl_add_u64 v[76:77], v[76:77], 0, s[0:1]
	global_load_dword v76, v[76:77], off nt
	v_cndmask_b32_e64 v77, 0, 1, s[22:23]
	v_cmp_ne_u32_e64 s[0:1], 1, v77
	s_cbranch_vccnz .LBB0_56
	v_add_u32_e32 v3, s16, v7
	v_ashrrev_i32_e32 v14, 31, v3
	v_mul_lo_u32 v16, s30, v14
	v_mul_lo_u32 v17, s31, v3
	v_mad_u64_u32 v[14:15], s[18:19], s30, v3, 0
	v_add3_u32 v15, v15, v16, v17
	v_lshl_add_u64 v[14:15], v[14:15], 2, s[24:25]
	s_ashr_i32 s27, s26, 31
	v_lshl_add_u64 v[14:15], s[26:27], 2, v[14:15]
	v_mov_b32_e32 v3, v1
	v_lshl_add_u64 v[14:15], v[14:15], 0, v[2:3]
	s_lshl_b64 s[18:19], s[30:31], 3
	v_lshl_add_u64 v[16:17], v[14:15], 0, s[18:19]
	global_load_dword v3, v[14:15], off nt
	s_nop 0
	global_load_dword v14, v[16:17], off nt
	v_lshl_add_u64 v[16:17], v[16:17], 0, s[18:19]
	v_lshl_add_u64 v[18:19], v[16:17], 0, s[18:19]
	global_load_dword v15, v[16:17], off nt
	s_nop 0
	global_load_dword v16, v[18:19], off nt
	v_lshl_add_u64 v[18:19], v[18:19], 0, s[18:19]
	v_lshl_add_u64 v[20:21], v[18:19], 0, s[18:19]
	global_load_dword v17, v[18:19], off nt
	s_nop 0
	global_load_dword v18, v[20:21], off nt
	v_lshl_add_u64 v[20:21], v[20:21], 0, s[18:19]
	v_lshl_add_u64 v[22:23], v[20:21], 0, s[18:19]
	global_load_dword v19, v[20:21], off nt
	s_nop 0
	global_load_dword v20, v[22:23], off nt
	v_lshl_add_u64 v[22:23], v[22:23], 0, s[18:19]
	v_lshl_add_u64 v[24:25], v[22:23], 0, s[18:19]
	global_load_dword v21, v[22:23], off nt
	s_nop 0
	global_load_dword v22, v[24:25], off nt
	v_lshl_add_u64 v[24:25], v[24:25], 0, s[18:19]
	v_lshl_add_u64 v[26:27], v[24:25], 0, s[18:19]
	global_load_dword v23, v[24:25], off nt
	s_nop 0
	global_load_dword v24, v[26:27], off nt
	v_lshl_add_u64 v[26:27], v[26:27], 0, s[18:19]
	v_lshl_add_u64 v[28:29], v[26:27], 0, s[18:19]
	global_load_dword v25, v[26:27], off nt
	s_nop 0
	global_load_dword v26, v[28:29], off nt
	v_lshl_add_u64 v[28:29], v[28:29], 0, s[18:19]
	v_lshl_add_u64 v[30:31], v[28:29], 0, s[18:19]
	global_load_dword v27, v[28:29], off nt
	s_nop 0
	global_load_dword v28, v[30:31], off nt
	v_lshl_add_u64 v[30:31], v[30:31], 0, s[18:19]
	v_lshl_add_u64 v[32:33], v[30:31], 0, s[18:19]
	global_load_dword v29, v[30:31], off nt
	s_nop 0
	global_load_dword v30, v[32:33], off nt
	v_lshl_add_u64 v[32:33], v[32:33], 0, s[18:19]
	v_lshl_add_u64 v[34:35], v[32:33], 0, s[18:19]
	global_load_dword v31, v[32:33], off nt
	s_nop 0
	global_load_dword v32, v[34:35], off nt
	v_lshl_add_u64 v[34:35], v[34:35], 0, s[18:19]
	v_lshl_add_u64 v[36:37], v[34:35], 0, s[18:19]
	global_load_dword v33, v[34:35], off nt
	s_nop 0
	global_load_dword v34, v[36:37], off nt
	v_lshl_add_u64 v[36:37], v[36:37], 0, s[18:19]
	v_lshl_add_u64 v[38:39], v[36:37], 0, s[18:19]
	global_load_dword v35, v[36:37], off nt
	s_nop 0
	global_load_dword v36, v[38:39], off nt
	v_lshl_add_u64 v[38:39], v[38:39], 0, s[18:19]
	v_lshl_add_u64 v[40:41], v[38:39], 0, s[18:19]
	global_load_dword v37, v[38:39], off nt
	s_nop 0
	global_load_dword v38, v[40:41], off nt
	v_lshl_add_u64 v[40:41], v[40:41], 0, s[18:19]
	v_lshl_add_u64 v[42:43], v[40:41], 0, s[18:19]
	global_load_dword v39, v[40:41], off nt
	s_nop 0
	global_load_dword v40, v[42:43], off nt
	v_lshl_add_u64 v[42:43], v[42:43], 0, s[18:19]
	v_lshl_add_u64 v[78:79], v[42:43], 0, s[18:19]
	global_load_dword v41, v[42:43], off nt
	s_nop 0
	global_load_dword v42, v[78:79], off nt
	v_lshl_add_u64 v[78:79], v[78:79], 0, s[18:19]
	global_load_dword v43, v[78:79], off nt
	v_lshl_add_u64 v[78:79], v[78:79], 0, s[18:19]
	global_load_dword v44, v[78:79], off nt
